# P0 x-row conversion fast path: 5 rows of loads in flight, cvt_pk packing, DPP row sum
# speedup vs baseline: 1.0717x; 1.0006x over previous
; __device__ __forceinline__ unsigned pk2(float lo, float hi) { return f2bf(lo) | (f2bf(hi) << 16); }
; __device__ __forceinline__ void phase0(CArgsP a, LAS unsigned char* lds, int wave, int lane) {
;     ...
;     {
;         bf16_t* XB = (bf16_t*)(ws + WS_XB); float* rq0 = (float*)(ws + WS_ROWSQ0); float* rq1 = (float*)(ws + WS_ROWSQ1); float* rq2 = (float*)(ws + WS_ROWSQ2);
; #pragma unroll 2
;         for (int m = gw; m < MROWS; m += NGW) {
;             const float* xrow = m < TP ? a->in[0] + (size_t)m * DM : a->in[1] + (size_t)(m - TP) * DM;
;             const f32x4* xr = (const f32x4*)xrow + lane; f32x4 v[4]; float s = 0.f;
; #pragma unroll
;             for (int j = 0; j < 4; ++j) { v[j] = xr[64 * j]; s += (v[j].x * v[j].x + v[j].y * v[j].y) + (v[j].z * v[j].z + v[j].w * v[j].w); }
;             s = wave_sum(s);
;             u32x2* o8 = (u32x2*)(XB + (size_t)m * DM) + lane;
; #pragma unroll
;             for (int j = 0; j < 4; ++j) { u32x2 w; w.x = pk2(v[j].x, v[j].y); w.y = pk2(v[j].z, v[j].w); o8[64 * j] = w; }
;             if (lane == 0) { rq0[m] = s; rq1[m] = 0.f; rq2[m] = 0.f; }
;         }
.LBB0_56:
	s_or_b64 exec, exec, s[4:5]
	s_lshl_b32 s0, s2, 3
	s_add_i32 s86, s79, s0
	s_lshl_b32 s34, s60, 3
	s_cmpk_lt_i32 s86, 0x4100
	s_cselect_b64 s[88:89], -1, 0
	s_cmpk_gt_i32 s86, 0x40ff
	v_mbcnt_lo_u32_b32 v151, -1, 0
	v_cmp_eq_u32_e64 s[4:5], 0, v148
	v_writelane_b32 v250, s0, 2
	s_cbranch_scc1 .LBB0_65
	s_cmpk_lg_i32 s60, 0x100
	s_cbranch_scc1 .Lxr_generic
	s_ashr_i32 s87, s86, 31
	s_ashr_i32 s35, s34, 31
	s_load_dwordx4 s[24:27], s[18:19], 0x0
	v_lshlrev_b32_e32 v117, 5, v148
	v_lshlrev_b32_e32 v118, 4, v148
	v_mov_b32_e32 v116, 0
	v_mov_b32_e32 v120, 0x20000
	v_mov_b32_e32 v144, 0x40000
	s_mov_b32 s14, 0
	s_brev_b32 s15, 1
	s_lshl_b32 s0, s86, 12
	s_waitcnt lgkmcnt(0)
	s_add_u32 s20, s24, s0
	s_addc_u32 s21, s25, 0
	s_add_u32 s22, s26, s0
	s_addc_u32 s23, s27, 0
	s_lshl_b32 s0, s86, 11
	s_add_u32 s28, s16, 0x2f00000
	s_addc_u32 s29, s17, 0
	s_add_u32 s28, s28, s0
	s_addc_u32 s29, s29, 0
	s_lshl_b32 s0, s86, 2
	s_add_u32 s12, s16, s0
	s_addc_u32 s13, s17, 0
	global_load_dwordx4 v[4:7], v117, s[20:21]
	global_load_dwordx4 v[8:11], v117, s[20:21] offset:16
	global_load_dwordx4 v[12:15], v117, s[20:21] offset:2048
	global_load_dwordx4 v[16:19], v117, s[20:21] offset:2064
	s_add_u32 s20, s20, 0x800000
	s_addc_u32 s21, s21, 0
	global_load_dwordx4 v[20:23], v117, s[20:21]
	global_load_dwordx4 v[24:27], v117, s[20:21] offset:16
	global_load_dwordx4 v[28:31], v117, s[20:21] offset:2048
	global_load_dwordx4 v[32:35], v117, s[20:21] offset:2064
	s_add_u32 s20, s20, 0x800000
	s_addc_u32 s21, s21, 0
	global_load_dwordx4 v[36:39], v117, s[20:21]
	global_load_dwordx4 v[40:43], v117, s[20:21] offset:16
	global_load_dwordx4 v[44:47], v117, s[20:21] offset:2048
	global_load_dwordx4 v[48:51], v117, s[20:21] offset:2064
	s_add_u32 s20, s20, 0x800000
	s_addc_u32 s21, s21, 0
	global_load_dwordx4 v[64:67], v117, s[20:21]
	global_load_dwordx4 v[68:71], v117, s[20:21] offset:16
	global_load_dwordx4 v[72:75], v117, s[20:21] offset:2048
	global_load_dwordx4 v[76:79], v117, s[20:21] offset:2064
	s_add_u32 s20, s20, 0x800000
	s_addc_u32 s21, s21, 0
	global_load_dwordx4 v[100:103], v117, s[20:21]
	global_load_dwordx4 v[104:107], v117, s[20:21] offset:16
	global_load_dwordx4 v[108:111], v117, s[20:21] offset:2048
	global_load_dwordx4 v[112:115], v117, s[20:21] offset:2064
	s_add_u32 s20, s20, 0x800000
	s_addc_u32 s21, s21, 0
	s_waitcnt vmcnt(16)
	v_mul_f32_e32 v52, v4, v4
	v_fmac_f32_e32 v52, v5, v5
	v_fmac_f32_e32 v52, v6, v6
	v_fmac_f32_e32 v52, v7, v7
	v_fmac_f32_e32 v52, v8, v8
	v_fmac_f32_e32 v52, v9, v9
	v_fmac_f32_e32 v52, v10, v10
	v_fmac_f32_e32 v52, v11, v11
	v_fmac_f32_e32 v52, v12, v12
	v_fmac_f32_e32 v52, v13, v13
	v_fmac_f32_e32 v52, v14, v14
	v_fmac_f32_e32 v52, v15, v15
	v_fmac_f32_e32 v52, v16, v16
	v_fmac_f32_e32 v52, v17, v17
	v_fmac_f32_e32 v52, v18, v18
	v_fmac_f32_e32 v52, v19, v19
	v_cvt_pk_bf16_f32 v80, v4, v5
	v_cvt_pk_bf16_f32 v81, v6, v7
	v_add_f32_dpp v52, v52, v52 quad_perm:[1,0,3,2] row_mask:0xf bank_mask:0xf bound_ctrl:1
	v_cvt_pk_bf16_f32 v82, v8, v9
	v_cvt_pk_bf16_f32 v83, v10, v11
	v_add_f32_dpp v52, v52, v52 quad_perm:[2,3,0,1] row_mask:0xf bank_mask:0xf bound_ctrl:1
	v_cvt_pk_bf16_f32 v84, v12, v13
	v_cvt_pk_bf16_f32 v85, v14, v15
	v_add_f32_dpp v52, v52, v52 row_half_mirror row_mask:0xf bank_mask:0xf bound_ctrl:1
	v_cvt_pk_bf16_f32 v86, v16, v17
	v_cvt_pk_bf16_f32 v87, v18, v19
	v_add_f32_dpp v52, v52, v52 row_mirror row_mask:0xf bank_mask:0xf bound_ctrl:1
	v_mov_b32_e32 v53, 0
	global_store_dwordx4 v118, v[80:83], s[28:29]
	global_store_dwordx4 v118, v[84:87], s[28:29] offset:1024
	s_nop 0
	v_mov_b32_dpp v53, v52 row_bcast:15 row_mask:0xa bank_mask:0xf
	v_add_f32_e32 v52, v52, v53
	v_mov_b32_e32 v53, 0
	s_nop 1
	v_mov_b32_dpp v53, v52 row_bcast:31 row_mask:0xc bank_mask:0xf
	v_add_f32_e32 v52, v52, v53
	s_and_saveexec_b64 s[42:43], s[14:15]
	global_store_dword v116, v52, s[12:13]
	global_store_dword v120, v116, s[12:13]
	global_store_dword v144, v116, s[12:13]
	s_mov_b64 exec, s[42:43]
	s_add_u32 s28, s28, 0x400000
	s_addc_u32 s29, s29, 0
	s_add_u32 s12, s12, 0x2000
	s_addc_u32 s13, s13, 0
	global_load_dwordx4 v[4:7], v117, s[20:21]
	global_load_dwordx4 v[8:11], v117, s[20:21] offset:16
	global_load_dwordx4 v[12:15], v117, s[20:21] offset:2048
	global_load_dwordx4 v[16:19], v117, s[20:21] offset:2064
	s_add_u32 s20, s20, 0x800000
	s_addc_u32 s21, s21, 0
	s_waitcnt vmcnt(21)
	v_mul_f32_e32 v52, v20, v20
	v_fmac_f32_e32 v52, v21, v21
	v_fmac_f32_e32 v52, v22, v22
	v_fmac_f32_e32 v52, v23, v23
	v_fmac_f32_e32 v52, v24, v24
	v_fmac_f32_e32 v52, v25, v25
	v_fmac_f32_e32 v52, v26, v26
	v_fmac_f32_e32 v52, v27, v27
	v_fmac_f32_e32 v52, v28, v28
	v_fmac_f32_e32 v52, v29, v29
	v_fmac_f32_e32 v52, v30, v30
	v_fmac_f32_e32 v52, v31, v31
	v_fmac_f32_e32 v52, v32, v32
	v_fmac_f32_e32 v52, v33, v33
	v_fmac_f32_e32 v52, v34, v34
	v_fmac_f32_e32 v52, v35, v35
	v_cvt_pk_bf16_f32 v88, v20, v21
	v_cvt_pk_bf16_f32 v89, v22, v23
	v_add_f32_dpp v52, v52, v52 quad_perm:[1,0,3,2] row_mask:0xf bank_mask:0xf bound_ctrl:1
	v_cvt_pk_bf16_f32 v90, v24, v25
	v_cvt_pk_bf16_f32 v91, v26, v27
	v_add_f32_dpp v52, v52, v52 quad_perm:[2,3,0,1] row_mask:0xf bank_mask:0xf bound_ctrl:1
	v_cvt_pk_bf16_f32 v54, v28, v29
	v_cvt_pk_bf16_f32 v55, v30, v31
	v_add_f32_dpp v52, v52, v52 row_half_mirror row_mask:0xf bank_mask:0xf bound_ctrl:1
	v_cvt_pk_bf16_f32 v56, v32, v33
	v_cvt_pk_bf16_f32 v57, v34, v35
	v_add_f32_dpp v52, v52, v52 row_mirror row_mask:0xf bank_mask:0xf bound_ctrl:1
	v_mov_b32_e32 v53, 0
	global_store_dwordx4 v118, v[88:91], s[28:29]
	global_store_dwordx4 v118, v[54:57], s[28:29] offset:1024
	s_nop 0
	v_mov_b32_dpp v53, v52 row_bcast:15 row_mask:0xa bank_mask:0xf
	v_add_f32_e32 v52, v52, v53
	v_mov_b32_e32 v53, 0
	s_nop 1
	v_mov_b32_dpp v53, v52 row_bcast:31 row_mask:0xc bank_mask:0xf
	v_add_f32_e32 v52, v52, v53
	s_and_saveexec_b64 s[42:43], s[14:15]
	global_store_dword v116, v52, s[12:13]
	global_store_dword v120, v116, s[12:13]
	global_store_dword v144, v116, s[12:13]
	s_mov_b64 exec, s[42:43]
	s_add_u32 s28, s28, 0x400000
	s_addc_u32 s29, s29, 0
	s_add_u32 s12, s12, 0x2000
	s_addc_u32 s13, s13, 0
	global_load_dwordx4 v[20:23], v117, s[20:21]
	global_load_dwordx4 v[24:27], v117, s[20:21] offset:16
	global_load_dwordx4 v[28:31], v117, s[20:21] offset:2048
	global_load_dwordx4 v[32:35], v117, s[20:21] offset:2064
	s_add_u32 s20, s20, 0x800000
	s_addc_u32 s21, s21, 0
	s_waitcnt vmcnt(26)
; __device__ __forceinline__ unsigned pk2(float lo, float hi) { return f2bf(lo) | (f2bf(hi) << 16); }
; __device__ __forceinline__ void phase0(CArgsP a, LAS unsigned char* lds, int wave, int lane) {
;     ...
;     {
;         bf16_t* XB = (bf16_t*)(ws + WS_XB); float* rq0 = (float*)(ws + WS_ROWSQ0); float* rq1 = (float*)(ws + WS_ROWSQ1); float* rq2 = (float*)(ws + WS_ROWSQ2);
; #pragma unroll 2
;         for (int m = gw; m < MROWS; m += NGW) {
;             const float* xrow = m < TP ? a->in[0] + (size_t)m * DM : a->in[1] + (size_t)(m - TP) * DM;
;             const f32x4* xr = (const f32x4*)xrow + lane; f32x4 v[4]; float s = 0.f;
; #pragma unroll
;             for (int j = 0; j < 4; ++j) { v[j] = xr[64 * j]; s += (v[j].x * v[j].x + v[j].y * v[j].y) + (v[j].z * v[j].z + v[j].w * v[j].w); }
;             s = wave_sum(s);
;             u32x2* o8 = (u32x2*)(XB + (size_t)m * DM) + lane;
; #pragma unroll
;             for (int j = 0; j < 4; ++j) { u32x2 w; w.x = pk2(v[j].x, v[j].y); w.y = pk2(v[j].z, v[j].w); o8[64 * j] = w; }
;             if (lane == 0) { rq0[m] = s; rq1[m] = 0.f; rq2[m] = 0.f; }
;         }
	v_mul_f32_e32 v52, v36, v36
	v_fmac_f32_e32 v52, v37, v37
	v_fmac_f32_e32 v52, v38, v38
	v_fmac_f32_e32 v52, v39, v39
	v_fmac_f32_e32 v52, v40, v40
	v_fmac_f32_e32 v52, v41, v41
	v_fmac_f32_e32 v52, v42, v42
	v_fmac_f32_e32 v52, v43, v43
	v_fmac_f32_e32 v52, v44, v44
	v_fmac_f32_e32 v52, v45, v45
	v_fmac_f32_e32 v52, v46, v46
	v_fmac_f32_e32 v52, v47, v47
	v_fmac_f32_e32 v52, v48, v48
	v_fmac_f32_e32 v52, v49, v49
	v_fmac_f32_e32 v52, v50, v50
	v_fmac_f32_e32 v52, v51, v51
	v_cvt_pk_bf16_f32 v80, v36, v37
	v_cvt_pk_bf16_f32 v81, v38, v39
	v_add_f32_dpp v52, v52, v52 quad_perm:[1,0,3,2] row_mask:0xf bank_mask:0xf bound_ctrl:1
	v_cvt_pk_bf16_f32 v82, v40, v41
	v_cvt_pk_bf16_f32 v83, v42, v43
	v_add_f32_dpp v52, v52, v52 quad_perm:[2,3,0,1] row_mask:0xf bank_mask:0xf bound_ctrl:1
	v_cvt_pk_bf16_f32 v84, v44, v45
	v_cvt_pk_bf16_f32 v85, v46, v47
	v_add_f32_dpp v52, v52, v52 row_half_mirror row_mask:0xf bank_mask:0xf bound_ctrl:1
	v_cvt_pk_bf16_f32 v86, v48, v49
	v_cvt_pk_bf16_f32 v87, v50, v51
	v_add_f32_dpp v52, v52, v52 row_mirror row_mask:0xf bank_mask:0xf bound_ctrl:1
	v_mov_b32_e32 v53, 0
	global_store_dwordx4 v118, v[80:83], s[28:29]
	global_store_dwordx4 v118, v[84:87], s[28:29] offset:1024
	s_nop 0
	v_mov_b32_dpp v53, v52 row_bcast:15 row_mask:0xa bank_mask:0xf
	v_add_f32_e32 v52, v52, v53
	v_mov_b32_e32 v53, 0
	s_nop 1
	v_mov_b32_dpp v53, v52 row_bcast:31 row_mask:0xc bank_mask:0xf
	v_add_f32_e32 v52, v52, v53
	s_and_saveexec_b64 s[42:43], s[14:15]
	global_store_dword v116, v52, s[12:13]
	global_store_dword v120, v116, s[12:13]
	global_store_dword v144, v116, s[12:13]
	s_mov_b64 exec, s[42:43]
	s_add_u32 s28, s28, 0x400000
	s_addc_u32 s29, s29, 0
	s_add_u32 s12, s12, 0x2000
	s_addc_u32 s13, s13, 0
	global_load_dwordx4 v[36:39], v117, s[20:21]
	global_load_dwordx4 v[40:43], v117, s[20:21] offset:16
	global_load_dwordx4 v[44:47], v117, s[20:21] offset:2048
	global_load_dwordx4 v[48:51], v117, s[20:21] offset:2064
	s_waitcnt vmcnt(31)
	v_mul_f32_e32 v52, v64, v64
	v_fmac_f32_e32 v52, v65, v65
	v_fmac_f32_e32 v52, v66, v66
	v_fmac_f32_e32 v52, v67, v67
	v_fmac_f32_e32 v52, v68, v68
	v_fmac_f32_e32 v52, v69, v69
	v_fmac_f32_e32 v52, v70, v70
	v_fmac_f32_e32 v52, v71, v71
	v_fmac_f32_e32 v52, v72, v72
	v_fmac_f32_e32 v52, v73, v73
	v_fmac_f32_e32 v52, v74, v74
	v_fmac_f32_e32 v52, v75, v75
	v_fmac_f32_e32 v52, v76, v76
	v_fmac_f32_e32 v52, v77, v77
	v_fmac_f32_e32 v52, v78, v78
	v_fmac_f32_e32 v52, v79, v79
	v_cvt_pk_bf16_f32 v88, v64, v65
	v_cvt_pk_bf16_f32 v89, v66, v67
	v_add_f32_dpp v52, v52, v52 quad_perm:[1,0,3,2] row_mask:0xf bank_mask:0xf bound_ctrl:1
	v_cvt_pk_bf16_f32 v90, v68, v69
	v_cvt_pk_bf16_f32 v91, v70, v71
	v_add_f32_dpp v52, v52, v52 quad_perm:[2,3,0,1] row_mask:0xf bank_mask:0xf bound_ctrl:1
	v_cvt_pk_bf16_f32 v54, v72, v73
	v_cvt_pk_bf16_f32 v55, v74, v75
	v_add_f32_dpp v52, v52, v52 row_half_mirror row_mask:0xf bank_mask:0xf bound_ctrl:1
	v_cvt_pk_bf16_f32 v56, v76, v77
	v_cvt_pk_bf16_f32 v57, v78, v79
	v_add_f32_dpp v52, v52, v52 row_mirror row_mask:0xf bank_mask:0xf bound_ctrl:1
	v_mov_b32_e32 v53, 0
	global_store_dwordx4 v118, v[88:91], s[28:29]
	global_store_dwordx4 v118, v[54:57], s[28:29] offset:1024
	s_nop 0
	v_mov_b32_dpp v53, v52 row_bcast:15 row_mask:0xa bank_mask:0xf
	v_add_f32_e32 v52, v52, v53
	v_mov_b32_e32 v53, 0
	s_nop 1
	v_mov_b32_dpp v53, v52 row_bcast:31 row_mask:0xc bank_mask:0xf
	v_add_f32_e32 v52, v52, v53
	s_and_saveexec_b64 s[42:43], s[14:15]
	global_store_dword v116, v52, s[12:13]
	global_store_dword v120, v116, s[12:13]
	global_store_dword v144, v116, s[12:13]
	s_mov_b64 exec, s[42:43]
	s_add_u32 s28, s28, 0x400000
	s_addc_u32 s29, s29, 0
	s_add_u32 s12, s12, 0x2000
	s_addc_u32 s13, s13, 0
	s_cmpk_lt_u32 s86, 0x100
	s_cbranch_scc0 .Lxr_no8
	global_load_dwordx4 v[64:67], v117, s[22:23]
	global_load_dwordx4 v[68:71], v117, s[22:23] offset:16
	global_load_dwordx4 v[72:75], v117, s[22:23] offset:2048
	global_load_dwordx4 v[76:79], v117, s[22:23] offset:2064
.Lxr_no8:
	s_waitcnt vmcnt(32)
	v_mul_f32_e32 v52, v100, v100
	v_fmac_f32_e32 v52, v101, v101
	v_fmac_f32_e32 v52, v102, v102
	v_fmac_f32_e32 v52, v103, v103
	v_fmac_f32_e32 v52, v104, v104
	v_fmac_f32_e32 v52, v105, v105
	v_fmac_f32_e32 v52, v106, v106
	v_fmac_f32_e32 v52, v107, v107
	v_fmac_f32_e32 v52, v108, v108
	v_fmac_f32_e32 v52, v109, v109
	v_fmac_f32_e32 v52, v110, v110
	v_fmac_f32_e32 v52, v111, v111
	v_fmac_f32_e32 v52, v112, v112
	v_fmac_f32_e32 v52, v113, v113
	v_fmac_f32_e32 v52, v114, v114
	v_fmac_f32_e32 v52, v115, v115
	v_cvt_pk_bf16_f32 v80, v100, v101
	v_cvt_pk_bf16_f32 v81, v102, v103
	v_add_f32_dpp v52, v52, v52 quad_perm:[1,0,3,2] row_mask:0xf bank_mask:0xf bound_ctrl:1
	v_cvt_pk_bf16_f32 v82, v104, v105
	v_cvt_pk_bf16_f32 v83, v106, v107
	v_add_f32_dpp v52, v52, v52 quad_perm:[2,3,0,1] row_mask:0xf bank_mask:0xf bound_ctrl:1
	v_cvt_pk_bf16_f32 v84, v108, v109
	v_cvt_pk_bf16_f32 v85, v110, v111
	v_add_f32_dpp v52, v52, v52 row_half_mirror row_mask:0xf bank_mask:0xf bound_ctrl:1
	v_cvt_pk_bf16_f32 v86, v112, v113
	v_cvt_pk_bf16_f32 v87, v114, v115
	v_add_f32_dpp v52, v52, v52 row_mirror row_mask:0xf bank_mask:0xf bound_ctrl:1
	v_mov_b32_e32 v53, 0
	global_store_dwordx4 v118, v[80:83], s[28:29]
	global_store_dwordx4 v118, v[84:87], s[28:29] offset:1024
	s_nop 0
	v_mov_b32_dpp v53, v52 row_bcast:15 row_mask:0xa bank_mask:0xf
	v_add_f32_e32 v52, v52, v53
	v_mov_b32_e32 v53, 0
	s_nop 1
	v_mov_b32_dpp v53, v52 row_bcast:31 row_mask:0xc bank_mask:0xf
	v_add_f32_e32 v52, v52, v53
	s_and_saveexec_b64 s[42:43], s[14:15]
	global_store_dword v116, v52, s[12:13]
	global_store_dword v120, v116, s[12:13]
	global_store_dword v144, v116, s[12:13]
	s_mov_b64 exec, s[42:43]
	s_add_u32 s28, s28, 0x400000
	s_addc_u32 s29, s29, 0
	s_add_u32 s12, s12, 0x2000
	s_addc_u32 s13, s13, 0
	s_waitcnt vmcnt(28)
; __device__ __forceinline__ unsigned pk2(float lo, float hi) { return f2bf(lo) | (f2bf(hi) << 16); }
; __device__ __forceinline__ void phase0(CArgsP a, LAS unsigned char* lds, int wave, int lane) {
;     ...
;     {
;         bf16_t* XB = (bf16_t*)(ws + WS_XB); float* rq0 = (float*)(ws + WS_ROWSQ0); float* rq1 = (float*)(ws + WS_ROWSQ1); float* rq2 = (float*)(ws + WS_ROWSQ2);
; #pragma unroll 2
;         for (int m = gw; m < MROWS; m += NGW) {
;             const float* xrow = m < TP ? a->in[0] + (size_t)m * DM : a->in[1] + (size_t)(m - TP) * DM;
;             const f32x4* xr = (const f32x4*)xrow + lane; f32x4 v[4]; float s = 0.f;
; #pragma unroll
;             for (int j = 0; j < 4; ++j) { v[j] = xr[64 * j]; s += (v[j].x * v[j].x + v[j].y * v[j].y) + (v[j].z * v[j].z + v[j].w * v[j].w); }
;             s = wave_sum(s);
;             u32x2* o8 = (u32x2*)(XB + (size_t)m * DM) + lane;
; #pragma unroll
;             for (int j = 0; j < 4; ++j) { u32x2 w; w.x = pk2(v[j].x, v[j].y); w.y = pk2(v[j].z, v[j].w); o8[64 * j] = w; }
;             if (lane == 0) { rq0[m] = s; rq1[m] = 0.f; rq2[m] = 0.f; }
;         }
	v_mul_f32_e32 v52, v4, v4
	v_fmac_f32_e32 v52, v5, v5
	v_fmac_f32_e32 v52, v6, v6
	v_fmac_f32_e32 v52, v7, v7
	v_fmac_f32_e32 v52, v8, v8
	v_fmac_f32_e32 v52, v9, v9
	v_fmac_f32_e32 v52, v10, v10
	v_fmac_f32_e32 v52, v11, v11
	v_fmac_f32_e32 v52, v12, v12
	v_fmac_f32_e32 v52, v13, v13
	v_fmac_f32_e32 v52, v14, v14
	v_fmac_f32_e32 v52, v15, v15
	v_fmac_f32_e32 v52, v16, v16
	v_fmac_f32_e32 v52, v17, v17
	v_fmac_f32_e32 v52, v18, v18
	v_fmac_f32_e32 v52, v19, v19
	v_cvt_pk_bf16_f32 v88, v4, v5
	v_cvt_pk_bf16_f32 v89, v6, v7
	v_add_f32_dpp v52, v52, v52 quad_perm:[1,0,3,2] row_mask:0xf bank_mask:0xf bound_ctrl:1
	v_cvt_pk_bf16_f32 v90, v8, v9
	v_cvt_pk_bf16_f32 v91, v10, v11
	v_add_f32_dpp v52, v52, v52 quad_perm:[2,3,0,1] row_mask:0xf bank_mask:0xf bound_ctrl:1
	v_cvt_pk_bf16_f32 v54, v12, v13
	v_cvt_pk_bf16_f32 v55, v14, v15
	v_add_f32_dpp v52, v52, v52 row_half_mirror row_mask:0xf bank_mask:0xf bound_ctrl:1
	v_cvt_pk_bf16_f32 v56, v16, v17
	v_cvt_pk_bf16_f32 v57, v18, v19
	v_add_f32_dpp v52, v52, v52 row_mirror row_mask:0xf bank_mask:0xf bound_ctrl:1
	v_mov_b32_e32 v53, 0
	global_store_dwordx4 v118, v[88:91], s[28:29]
	global_store_dwordx4 v118, v[54:57], s[28:29] offset:1024
	s_nop 0
	v_mov_b32_dpp v53, v52 row_bcast:15 row_mask:0xa bank_mask:0xf
	v_add_f32_e32 v52, v52, v53
	v_mov_b32_e32 v53, 0
	s_nop 1
	v_mov_b32_dpp v53, v52 row_bcast:31 row_mask:0xc bank_mask:0xf
	v_add_f32_e32 v52, v52, v53
	s_and_saveexec_b64 s[42:43], s[14:15]
	global_store_dword v116, v52, s[12:13]
	global_store_dword v120, v116, s[12:13]
	global_store_dword v144, v116, s[12:13]
	s_mov_b64 exec, s[42:43]
	s_add_u32 s28, s28, 0x400000
	s_addc_u32 s29, s29, 0
	s_add_u32 s12, s12, 0x2000
	s_addc_u32 s13, s13, 0
	s_waitcnt vmcnt(24)
	v_mul_f32_e32 v52, v20, v20
	v_fmac_f32_e32 v52, v21, v21
	v_fmac_f32_e32 v52, v22, v22
	v_fmac_f32_e32 v52, v23, v23
	v_fmac_f32_e32 v52, v24, v24
	v_fmac_f32_e32 v52, v25, v25
	v_fmac_f32_e32 v52, v26, v26
	v_fmac_f32_e32 v52, v27, v27
	v_fmac_f32_e32 v52, v28, v28
	v_fmac_f32_e32 v52, v29, v29
	v_fmac_f32_e32 v52, v30, v30
	v_fmac_f32_e32 v52, v31, v31
	v_fmac_f32_e32 v52, v32, v32
	v_fmac_f32_e32 v52, v33, v33
	v_fmac_f32_e32 v52, v34, v34
	v_fmac_f32_e32 v52, v35, v35
	v_cvt_pk_bf16_f32 v80, v20, v21
	v_cvt_pk_bf16_f32 v81, v22, v23
	v_add_f32_dpp v52, v52, v52 quad_perm:[1,0,3,2] row_mask:0xf bank_mask:0xf bound_ctrl:1
	v_cvt_pk_bf16_f32 v82, v24, v25
	v_cvt_pk_bf16_f32 v83, v26, v27
	v_add_f32_dpp v52, v52, v52 quad_perm:[2,3,0,1] row_mask:0xf bank_mask:0xf bound_ctrl:1
	v_cvt_pk_bf16_f32 v84, v28, v29
	v_cvt_pk_bf16_f32 v85, v30, v31
	v_add_f32_dpp v52, v52, v52 row_half_mirror row_mask:0xf bank_mask:0xf bound_ctrl:1
	v_cvt_pk_bf16_f32 v86, v32, v33
	v_cvt_pk_bf16_f32 v87, v34, v35
	v_add_f32_dpp v52, v52, v52 row_mirror row_mask:0xf bank_mask:0xf bound_ctrl:1
	v_mov_b32_e32 v53, 0
	global_store_dwordx4 v118, v[80:83], s[28:29]
	global_store_dwordx4 v118, v[84:87], s[28:29] offset:1024
	s_nop 0
	v_mov_b32_dpp v53, v52 row_bcast:15 row_mask:0xa bank_mask:0xf
	v_add_f32_e32 v52, v52, v53
	v_mov_b32_e32 v53, 0
	s_nop 1
	v_mov_b32_dpp v53, v52 row_bcast:31 row_mask:0xc bank_mask:0xf
	v_add_f32_e32 v52, v52, v53
	s_and_saveexec_b64 s[42:43], s[14:15]
	global_store_dword v116, v52, s[12:13]
	global_store_dword v120, v116, s[12:13]
	global_store_dword v144, v116, s[12:13]
	s_mov_b64 exec, s[42:43]
	s_add_u32 s28, s28, 0x400000
	s_addc_u32 s29, s29, 0
	s_add_u32 s12, s12, 0x2000
	s_addc_u32 s13, s13, 0
	s_waitcnt vmcnt(20)
	v_mul_f32_e32 v52, v36, v36
	v_fmac_f32_e32 v52, v37, v37
	v_fmac_f32_e32 v52, v38, v38
	v_fmac_f32_e32 v52, v39, v39
	v_fmac_f32_e32 v52, v40, v40
	v_fmac_f32_e32 v52, v41, v41
	v_fmac_f32_e32 v52, v42, v42
	v_fmac_f32_e32 v52, v43, v43
	v_fmac_f32_e32 v52, v44, v44
	v_fmac_f32_e32 v52, v45, v45
	v_fmac_f32_e32 v52, v46, v46
	v_fmac_f32_e32 v52, v47, v47
	v_fmac_f32_e32 v52, v48, v48
	v_fmac_f32_e32 v52, v49, v49
	v_fmac_f32_e32 v52, v50, v50
	v_fmac_f32_e32 v52, v51, v51
	v_cvt_pk_bf16_f32 v88, v36, v37
	v_cvt_pk_bf16_f32 v89, v38, v39
	v_add_f32_dpp v52, v52, v52 quad_perm:[1,0,3,2] row_mask:0xf bank_mask:0xf bound_ctrl:1
	v_cvt_pk_bf16_f32 v90, v40, v41
	v_cvt_pk_bf16_f32 v91, v42, v43
	v_add_f32_dpp v52, v52, v52 quad_perm:[2,3,0,1] row_mask:0xf bank_mask:0xf bound_ctrl:1
	v_cvt_pk_bf16_f32 v54, v44, v45
	v_cvt_pk_bf16_f32 v55, v46, v47
	v_add_f32_dpp v52, v52, v52 row_half_mirror row_mask:0xf bank_mask:0xf bound_ctrl:1
	v_cvt_pk_bf16_f32 v56, v48, v49
	v_cvt_pk_bf16_f32 v57, v50, v51
	v_add_f32_dpp v52, v52, v52 row_mirror row_mask:0xf bank_mask:0xf bound_ctrl:1
	v_mov_b32_e32 v53, 0
	global_store_dwordx4 v118, v[88:91], s[28:29]
	global_store_dwordx4 v118, v[54:57], s[28:29] offset:1024
	s_nop 0
	v_mov_b32_dpp v53, v52 row_bcast:15 row_mask:0xa bank_mask:0xf
	v_add_f32_e32 v52, v52, v53
	v_mov_b32_e32 v53, 0
	s_nop 1
	v_mov_b32_dpp v53, v52 row_bcast:31 row_mask:0xc bank_mask:0xf
	v_add_f32_e32 v52, v52, v53
	s_and_saveexec_b64 s[42:43], s[14:15]
	global_store_dword v116, v52, s[12:13]
	global_store_dword v120, v116, s[12:13]
	global_store_dword v144, v116, s[12:13]
	s_mov_b64 exec, s[42:43]
	s_add_u32 s28, s28, 0x400000
	s_addc_u32 s29, s29, 0
	s_add_u32 s12, s12, 0x2000
	s_addc_u32 s13, s13, 0
	s_cmpk_lt_u32 s86, 0x100
	s_cbranch_scc0 .Lxr_done
	s_waitcnt vmcnt(20)
	v_mul_f32_e32 v52, v64, v64
	v_fmac_f32_e32 v52, v65, v65
	v_fmac_f32_e32 v52, v66, v66
	v_fmac_f32_e32 v52, v67, v67
	v_fmac_f32_e32 v52, v68, v68
	v_fmac_f32_e32 v52, v69, v69
	v_fmac_f32_e32 v52, v70, v70
	v_fmac_f32_e32 v52, v71, v71
	v_fmac_f32_e32 v52, v72, v72
	v_fmac_f32_e32 v52, v73, v73
	v_fmac_f32_e32 v52, v74, v74
	v_fmac_f32_e32 v52, v75, v75
	v_fmac_f32_e32 v52, v76, v76
	v_fmac_f32_e32 v52, v77, v77
	v_fmac_f32_e32 v52, v78, v78
	v_fmac_f32_e32 v52, v79, v79
	v_cvt_pk_bf16_f32 v80, v64, v65
	v_cvt_pk_bf16_f32 v81, v66, v67
	v_add_f32_dpp v52, v52, v52 quad_perm:[1,0,3,2] row_mask:0xf bank_mask:0xf bound_ctrl:1
	v_cvt_pk_bf16_f32 v82, v68, v69
	v_cvt_pk_bf16_f32 v83, v70, v71
	v_add_f32_dpp v52, v52, v52 quad_perm:[2,3,0,1] row_mask:0xf bank_mask:0xf bound_ctrl:1
	v_cvt_pk_bf16_f32 v84, v72, v73
	v_cvt_pk_bf16_f32 v85, v74, v75
	v_add_f32_dpp v52, v52, v52 row_half_mirror row_mask:0xf bank_mask:0xf bound_ctrl:1
	v_cvt_pk_bf16_f32 v86, v76, v77
	v_cvt_pk_bf16_f32 v87, v78, v79
	v_add_f32_dpp v52, v52, v52 row_mirror row_mask:0xf bank_mask:0xf bound_ctrl:1
	v_mov_b32_e32 v53, 0
	global_store_dwordx4 v118, v[80:83], s[28:29]
	global_store_dwordx4 v118, v[84:87], s[28:29] offset:1024
	s_nop 0
	v_mov_b32_dpp v53, v52 row_bcast:15 row_mask:0xa bank_mask:0xf
	v_add_f32_e32 v52, v52, v53
	v_mov_b32_e32 v53, 0
	s_nop 1
	v_mov_b32_dpp v53, v52 row_bcast:31 row_mask:0xc bank_mask:0xf
	v_add_f32_e32 v52, v52, v53
	s_and_saveexec_b64 s[42:43], s[14:15]
	global_store_dword v116, v52, s[12:13]
	global_store_dword v120, v116, s[12:13]
	global_store_dword v144, v116, s[12:13]
	s_mov_b64 exec, s[42:43]

; __device__ __forceinline__ float wave_sum(float v) {
; #pragma unroll
;     for (int o = 1; o < 64; o <<= 1) v += __shfl_xor(v, o);
;     return v;
; }
; __device__ __forceinline__ void phase0(CArgsP a, LAS unsigned char* lds, int wave, int lane) {
;     ...
;     {
;         bf16_t* XB = (bf16_t*)(ws + WS_XB); float* rq0 = (float*)(ws + WS_ROWSQ0); float* rq1 = (float*)(ws + WS_ROWSQ1); float* rq2 = (float*)(ws + WS_ROWSQ2);
; #pragma unroll 2
;         for (int m = gw; m < MROWS; m += NGW) {
;             const float* xrow = m < TP ? a->in[0] + (size_t)m * DM : a->in[1] + (size_t)(m - TP) * DM;
;             const f32x4* xr = (const f32x4*)xrow + lane; f32x4 v[4]; float s = 0.f;
; #pragma unroll
;             for (int j = 0; j < 4; ++j) { v[j] = xr[64 * j]; s += (v[j].x * v[j].x + v[j].y * v[j].y) + (v[j].z * v[j].z + v[j].w * v[j].w); }
;             s = wave_sum(s);
;             u32x2* o8 = (u32x2*)(XB + (size_t)m * DM) + lane;
.Lxr_generic:
	v_mbcnt_hi_u32_b32 v2, -1, v151
	v_and_b32_e32 v1, 64, v2
	v_add_u32_e32 v4, 64, v1
	v_xor_b32_e32 v1, 1, v2
	v_cmp_lt_i32_e32 vcc, v1, v4
	v_xor_b32_e32 v5, 2, v2
	s_add_u32 s0, s16, 0x20000
	v_cndmask_b32_e32 v1, v2, v1, vcc
	v_cmp_lt_i32_e32 vcc, v5, v4
	s_addc_u32 s1, s17, 0
	s_add_u32 s3, s16, 0x40000
	v_cndmask_b32_e32 v5, v2, v5, vcc
	v_lshlrev_b32_e32 v6, 2, v5
	v_xor_b32_e32 v5, 4, v2
	v_cmp_lt_i32_e32 vcc, v5, v4
	v_mov_b32_e32 v3, 0
	s_addc_u32 s6, s17, 0
	v_cndmask_b32_e32 v5, v2, v5, vcc
	v_lshlrev_b32_e32 v7, 2, v5
	v_xor_b32_e32 v5, 8, v2
	v_cmp_lt_i32_e32 vcc, v5, v4
	s_mov_b64 s[14:15], 0x2f00000
	s_ashr_i32 s87, s86, 31
	v_cndmask_b32_e32 v5, v2, v5, vcc
	v_lshlrev_b32_e32 v8, 2, v5
	v_xor_b32_e32 v5, 16, v2
	v_cmp_lt_i32_e32 vcc, v5, v4
	s_ashr_i32 s35, s34, 31
	s_mov_b32 s13, 0
	v_cndmask_b32_e32 v5, v2, v5, vcc
	v_lshlrev_b32_e32 v9, 2, v5
	v_xor_b32_e32 v5, 32, v2
	v_cmp_lt_i32_e32 vcc, v5, v4
	v_lshlrev_b32_e32 v1, 2, v1
	s_lshl_b64 s[20:21], s[34:35], 12
	v_cndmask_b32_e32 v2, v2, v5, vcc
	v_lshlrev_b32_e32 v10, 2, v2
	v_lshlrev_b32_e32 v2, 3, v148
	v_lshl_add_u64 v[4:5], s[16:17], 0, v[2:3]
	v_lshl_add_u64 v[4:5], v[4:5], 0, s[14:15]
	s_lshl_b64 s[14:15], s[86:87], 12
	v_lshlrev_b32_e32 v2, 4, v148
	s_movk_i32 s7, 0x7fff
	s_mov_b32 s30, 0xffff0000
	s_mov_b64 s[22:23], s[86:87]
	s_branch .LBB0_59
